# P0 rmsnorm row loop: pre_norm weight loads hoisted out of the loop (they were reloaded per iteration behind full vmcnt(0) drains)
# speedup vs baseline: 1.0179x; 1.0092x over previous
; #define GAS __attribute__((address_space(1)))
; __device__ __forceinline__ int opq(int v) { asm volatile("" : "+s"(v)); return v; }
; __device__ __forceinline__ void rms_row2_1024(const GAS float* x0, const GAS float* x1, const GAS float* g, GAS bf16_t* o0, GAS bf16_t* o1, int lane) {
;     const GAS f32x4* xr0 = (const GAS f32x4*)x0 + lane; const GAS f32x4* xr1 = (const GAS f32x4*)x1 + lane; const GAS f32x4* gr = (const GAS f32x4*)g + lane;
;     f32x4 v[4], w[4]; float s = 0.f, s2 = 0.f;
; #pragma unroll
;     for (int j = 0; j < 4; ++j) { v[j] = __builtin_nontemporal_load(xr0 + 64 * j); w[j] = __builtin_nontemporal_load(xr1 + 64 * j); }
; #pragma unroll
;     for (int j = 0; j < 4; ++j) { s += (v[j].x * v[j].x + v[j].y * v[j].y) + (v[j].z * v[j].z + v[j].w * v[j].w); s2 += (w[j].x * w[j].x + w[j].y * w[j].y) + (w[j].z * w[j].z + w[j].w * w[j].w); }
; #pragma unroll
;     for (int o = 1; o < 64; o <<= 1) { s += __shfl_xor(s, o); s2 += __shfl_xor(s2, o); }
;     const float r0 = 1.f / sqrtf(s * (1.f / 1024.f) + NORM_EPS), r1 = 1.f / sqrtf(s2 * (1.f / 1024.f) + NORM_EPS);
;     GAS u32x2* p0 = (GAS u32x2*)o0 + lane; GAS u32x2* p1 = (GAS u32x2*)o1 + lane;
; #pragma unroll
;     for (int j = 0; j < 4; ++j) { const f32x4 gg = gr[64 * j]; u32x2 a, b;
;         a.x = pk2(v[j].x * r0 * gg.x, v[j].y * r0 * gg.y); a.y = pk2(v[j].z * r0 * gg.z, v[j].w * r0 * gg.w);
;         b.x = pk2(w[j].x * r1 * gg.x, w[j].y * r1 * gg.y); b.y = pk2(w[j].z * r1 * gg.z, w[j].w * r1 * gg.w);
;         p0[64 * j] = a; p1[64 * j] = b; }
; }
; __global__ void __launch_bounds__(512, 2) fwd_mega(Args a) {
;     ...
;         { const GAS float* xin = ((const GAS float*)a.in[opq(I_X)]); const GAS float* gin = ((const GAS float*)a.in[opq(I_PRENORM)]);
;           for (int m = gw; m < TOK; m += 2 * NGW) rms_row2_1024(xin + (size_t)m * 1024, xin + (size_t)(m + NGW) * 1024, gin, H + (size_t)m * 1024, H + (size_t)(m + NGW) * 1024, lane); }
.LBB0_79:
	s_or_b64 exec, exec, s[6:7]
	s_cmp_lt_i32 s16, 0x8000
	s_cselect_b64 s[24:25], -1, 0
	s_mov_b32 s8, 0
	s_mov_b32 s6, 3
	v_writelane_b32 v240, s24, 0
	s_cmpk_gt_i32 s16, 0x7fff
	v_ashrrev_i32_e32 v33, 31, v32
	v_and_b32_e32 v187, 64, v184
	v_xor_b32_e32 v186, 16, v184
	v_xor_b32_e32 v185, 32, v184
	v_writelane_b32 v240, s25, 1
	s_cbranch_scc1 .LBB0_82
	v_add_u32_e32 v2, 64, v187
	v_xor_b32_e32 v3, 1, v184
	v_cmp_lt_i32_e32 vcc, v3, v2
	s_ashr_i32 s9, s8, 31
	s_lshl_b64 s[8:9], s[8:9], 3
	v_cndmask_b32_e32 v3, v184, v3, vcc
	v_lshlrev_b32_e32 v42, 2, v3
	v_xor_b32_e32 v3, 2, v184
	s_add_u32 s8, s0, s8
	v_cmp_lt_i32_e32 vcc, v3, v2
	s_addc_u32 s9, s1, s9
	s_ashr_i32 s7, s6, 31
	v_cndmask_b32_e32 v3, v184, v3, vcc
	s_lshl_b64 s[6:7], s[6:7], 3
	v_lshlrev_b32_e32 v43, 2, v3
	v_xor_b32_e32 v3, 4, v184
	s_add_u32 s6, s0, s6
	v_cmp_lt_i32_e32 vcc, v3, v2
	s_addc_u32 s7, s1, s7
	s_load_dwordx2 s[8:9], s[8:9], 0x0
	v_cndmask_b32_e32 v3, v184, v3, vcc
	s_load_dwordx2 s[6:7], s[6:7], 0x0
	v_lshlrev_b32_e32 v44, 2, v3
	v_xor_b32_e32 v3, 8, v184
	v_cmp_lt_i32_e32 vcc, v3, v2
	v_lshlrev_b64 v[0:1], 4, v[32:33]
	s_waitcnt lgkmcnt(0)
	v_lshl_add_u64 v[36:37], s[8:9], 0, v[0:1]
	v_cndmask_b32_e32 v3, v184, v3, vcc
	v_cmp_lt_i32_e32 vcc, v186, v2
	v_lshlrev_b32_e32 v45, 2, v3
	v_lshl_add_u64 v[38:39], s[6:7], 0, v[0:1]
	v_cndmask_b32_e32 v3, v184, v186, vcc
	v_cmp_lt_i32_e32 vcc, v185, v2
	v_lshlrev_b32_e32 v46, 2, v3
	v_lshl_add_u64 v[40:41], v[32:33], 3, s[4:5]
	v_cndmask_b32_e32 v2, v184, v185, vcc
	v_lshlrev_b32_e32 v47, 2, v2
	v_mov_b32_e32 v48, 0x358637bd
	s_mov_b32 s17, 0xf800000
	v_mov_b32_e32 v49, 0x260
	s_mov_b32 s26, s16
	global_load_dwordx4 v[80:83], v[38:39], off
	global_load_dwordx4 v[84:87], v[38:39], off offset:1024
	global_load_dwordx4 v[88:91], v[38:39], off offset:2048
	global_load_dwordx4 v[92:95], v[38:39], off offset:3072
.LBB0_81:
	s_ashr_i32 s27, s26, 31
	s_lshl_b64 s[4:5], s[26:27], 12
	s_add_i32 s8, s26, s20
	v_lshl_add_u64 v[4:5], v[36:37], 0, s[4:5]
	s_ashr_i32 s9, s8, 31
	global_load_dwordx4 v[24:27], v[4:5], off nt
	global_load_dwordx4 v[16:19], v[4:5], off offset:1024 nt
	global_load_dwordx4 v[0:3], v[4:5], off offset:3072 nt
	global_load_dwordx4 v[12:15], v[4:5], off offset:2048 nt
	s_lshl_b64 s[4:5], s[8:9], 12
	v_lshl_add_u64 v[50:51], v[36:37], 0, s[4:5]
	global_load_dwordx4 v[28:31], v[50:51], off nt
	global_load_dwordx4 v[20:23], v[50:51], off offset:1024 nt
	global_load_dwordx4 v[4:7], v[50:51], off offset:3072 nt
	global_load_dwordx4 v[8:11], v[50:51], off offset:2048 nt
	s_waitcnt vmcnt(7)
	v_pk_mul_f32 v[50:51], v[26:27], v[26:27]
	v_pk_mul_f32 v[52:53], v[24:25], v[24:25]
	s_waitcnt vmcnt(6)
	v_pk_mul_f32 v[54:55], v[18:19], v[18:19]
	v_pk_mul_f32 v[56:57], v[16:17], v[16:17]
	s_waitcnt vmcnt(4)
	v_mul_f32_e32 v58, v13, v13
	v_mul_f32_e32 v60, v15, v15
	v_pk_mov_b32 v[62:63], v[52:53], v[50:51] op_sel:[1,0]
	v_mov_b32_e32 v53, v51
	s_waitcnt vmcnt(3)
	v_pk_mul_f32 v[50:51], v[30:31], v[30:31]
	v_pk_mul_f32 v[64:65], v[28:29], v[28:29]
	v_pk_mov_b32 v[66:67], v[56:57], v[54:55] op_sel:[1,0]
	v_mov_b32_e32 v57, v55
	s_waitcnt vmcnt(2)
	v_pk_mul_f32 v[54:55], v[22:23], v[22:23]
	v_pk_mul_f32 v[68:69], v[20:21], v[20:21]
	v_mul_f32_e32 v74, v2, v2
	v_mul_f32_e32 v75, v3, v3
	v_pk_fma_f32 v[58:59], v[12:13], v[12:13], v[58:59] op_sel_hi:[1,1,0]
	v_pk_fma_f32 v[60:61], v[14:15], v[14:15], v[60:61] op_sel_hi:[1,1,0]
	v_pk_add_f32 v[52:53], v[62:63], v[52:53]
	v_pk_mov_b32 v[62:63], v[64:65], v[50:51] op_sel:[1,0]
	v_mov_b32_e32 v65, v51
	v_pk_add_f32 v[50:51], v[66:67], v[56:57]
	v_pk_mov_b32 v[56:57], v[68:69], v[54:55] op_sel:[1,0]
	v_mov_b32_e32 v69, v55
	v_mul_f32_e32 v71, v0, v0
	v_mul_f32_e32 v73, v1, v1
	s_waitcnt vmcnt(0)
	v_mul_f32_e32 v70, v9, v9
	v_mul_f32_e32 v72, v11, v11
	v_mov_b32_e32 v59, v74
	v_mov_b32_e32 v61, v75
	v_pk_add_f32 v[62:63], v[62:63], v[64:65]
	v_pk_add_f32 v[56:57], v[56:57], v[68:69]
	v_pk_add_f32 v[52:53], v[52:53], v[52:53] op_sel:[0,1] op_sel_hi:[1,0]
	v_pk_add_f32 v[50:51], v[50:51], v[50:51] op_sel:[0,1] op_sel_hi:[1,0]
	v_mul_f32_e32 v76, v4, v4
	v_mul_f32_e32 v77, v5, v5
	v_mul_f32_e32 v78, v6, v6
	v_mul_f32_e32 v79, v7, v7
	v_pk_fma_f32 v[54:55], v[8:9], v[8:9], v[70:71] op_sel_hi:[1,1,0]
	v_pk_fma_f32 v[66:67], v[10:11], v[10:11], v[72:73] op_sel_hi:[1,1,0]
	v_pk_add_f32 v[58:59], v[58:59], v[60:61]
	v_mov_b32_e32 v53, v71
	v_mov_b32_e32 v51, v73
	v_pk_add_f32 v[60:61], v[62:63], v[62:63] op_sel:[0,1] op_sel_hi:[1,0]
	v_pk_add_f32 v[56:57], v[56:57], v[56:57] op_sel:[0,1] op_sel_hi:[1,0]
	v_mov_b32_e32 v55, v78
	v_mov_b32_e32 v67, v79
	v_pk_add_f32 v[50:51], v[52:53], v[50:51]
	v_mov_b32_e32 v61, v76
	v_mov_b32_e32 v57, v77
	v_pk_add_f32 v[54:55], v[54:55], v[66:67]
	v_pk_add_f32 v[50:51], v[50:51], v[58:59]
	v_pk_add_f32 v[52:53], v[60:61], v[56:57]
	v_add_f32_e32 v56, v50, v51
	v_pk_add_f32 v[50:51], v[52:53], v[54:55]
	s_nop 0
	v_add_f32_e32 v50, v50, v51
	ds_bpermute_b32 v51, v42, v56
	ds_bpermute_b32 v52, v42, v50
	s_waitcnt lgkmcnt(1)
	v_add_f32_e32 v51, v56, v51
	s_waitcnt lgkmcnt(0)
	v_add_f32_e32 v50, v50, v52
	ds_bpermute_b32 v52, v43, v51
	ds_bpermute_b32 v53, v43, v50
	s_waitcnt lgkmcnt(1)
	v_add_f32_e32 v51, v51, v52
	s_waitcnt lgkmcnt(0)
	v_add_f32_e32 v50, v50, v53
	ds_bpermute_b32 v52, v44, v51
	ds_bpermute_b32 v53, v44, v50
	s_waitcnt lgkmcnt(1)
; #define GAS __attribute__((address_space(1)))
; __device__ __forceinline__ void rms_row2_1024(const GAS float* x0, const GAS float* x1, const GAS float* g, GAS bf16_t* o0, GAS bf16_t* o1, int lane) {
;     ...
;     for (int j = 0; j < 4; ++j) { s += (v[j].x * v[j].x + v[j].y * v[j].y) + (v[j].z * v[j].z + v[j].w * v[j].w); s2 += (w[j].x * w[j].x + w[j].y * w[j].y) + (w[j].z * w[j].z + w[j].w * w[j].w); }
; #pragma unroll
;     for (int o = 1; o < 64; o <<= 1) { s += __shfl_xor(s, o); s2 += __shfl_xor(s2, o); }
;     const float r0 = 1.f / sqrtf(s * (1.f / 1024.f) + NORM_EPS), r1 = 1.f / sqrtf(s2 * (1.f / 1024.f) + NORM_EPS);
;     GAS u32x2* p0 = (GAS u32x2*)o0 + lane; GAS u32x2* p1 = (GAS u32x2*)o1 + lane;
; #pragma unroll
;     for (int j = 0; j < 4; ++j) { const f32x4 gg = gr[64 * j]; u32x2 a, b;
;         a.x = pk2(v[j].x * r0 * gg.x, v[j].y * r0 * gg.y); a.y = pk2(v[j].z * r0 * gg.z, v[j].w * r0 * gg.w);
;         b.x = pk2(w[j].x * r1 * gg.x, w[j].y * r1 * gg.y); b.y = pk2(w[j].z * r1 * gg.z, w[j].w * r1 * gg.w);
;         p0[64 * j] = a; p1[64 * j] = b; }
	v_add_f32_e32 v54, v51, v52
	s_waitcnt lgkmcnt(0)
	v_add_f32_e32 v55, v50, v53
	ds_bpermute_b32 v56, v45, v54
	ds_bpermute_b32 v57, v45, v55
	s_waitcnt lgkmcnt(1)
	v_add_f32_e32 v54, v54, v56
	ds_bpermute_b32 v56, v46, v54
	s_waitcnt lgkmcnt(1)
	v_add_f32_e32 v55, v55, v57
	ds_bpermute_b32 v57, v46, v55
	s_waitcnt lgkmcnt(1)
	v_add_f32_e32 v54, v54, v56
	ds_bpermute_b32 v56, v47, v54
	s_waitcnt lgkmcnt(1)
	v_add_f32_e32 v55, v55, v57
	ds_bpermute_b32 v57, v47, v55
	s_waitcnt lgkmcnt(1)
	v_add_f32_e32 v54, v54, v56
	v_fmamk_f32 v54, v54, 0x3a800000, v48
	s_waitcnt lgkmcnt(0)
	v_add_f32_e32 v55, v55, v57
	v_mul_f32_e32 v56, 0x4f800000, v54
	v_cmp_gt_f32_e32 vcc, s17, v54
	v_fmamk_f32 v55, v55, 0x3a800000, v48
	v_cmp_gt_f32_e64 s[4:5], s17, v55
	v_cndmask_b32_e32 v54, v54, v56, vcc
	v_mul_f32_e32 v56, 0x4f800000, v55
	v_sqrt_f32_e32 v57, v54
	v_cndmask_b32_e64 v55, v55, v56, s[4:5]
	v_sqrt_f32_e32 v56, v55
	v_add_u32_e32 v58, -1, v57
	v_add_u32_e32 v59, 1, v57
	v_fma_f32 v60, -v58, v57, v54
	v_fma_f32 v61, -v59, v57, v54
	v_add_u32_e32 v62, -1, v56
	v_cmp_ge_f32_e64 s[6:7], 0, v60
	v_add_u32_e32 v63, 1, v56
	v_fma_f32 v60, -v63, v56, v55
	v_cndmask_b32_e64 v57, v57, v58, s[6:7]
	v_fma_f32 v58, -v62, v56, v55
	v_cmp_lt_f32_e64 s[6:7], 0, v61
	s_nop 1
	v_cndmask_b32_e64 v57, v57, v59, s[6:7]
	v_cmp_ge_f32_e64 s[6:7], 0, v58
	v_mul_f32_e32 v58, 0x37800000, v57
	v_cndmask_b32_e32 v57, v57, v58, vcc
	v_cndmask_b32_e64 v56, v56, v62, s[6:7]
	v_cmp_lt_f32_e64 s[6:7], 0, v60
	v_cmp_class_f32_e32 vcc, v54, v49
	s_nop 0
	v_cndmask_b32_e64 v56, v56, v63, s[6:7]
	v_mul_f32_e32 v58, 0x37800000, v56
	v_cndmask_b32_e32 v54, v57, v54, vcc
	v_cndmask_b32_e64 v56, v56, v58, s[4:5]
	v_div_scale_f32 v57, s[4:5], v54, v54, 1.0
	v_cmp_class_f32_e64 s[4:5], v55, v49
	v_div_scale_f32 v58, vcc, 1.0, v54, 1.0
	s_nop 0
	v_cndmask_b32_e64 v55, v56, v55, s[4:5]
	v_rcp_f32_e32 v56, v57
	v_div_scale_f32 v59, s[4:5], v55, v55, 1.0
	v_rcp_f32_e32 v60, v59
	v_fma_f32 v62, -v57, v56, 1.0
	v_fmac_f32_e32 v56, v62, v56
	v_mul_f32_e32 v63, v58, v56
	v_fma_f32 v62, -v59, v60, 1.0
	v_div_scale_f32 v61, s[4:5], 1.0, v55, 1.0
	v_fmac_f32_e32 v60, v62, v60
	v_fma_f32 v62, -v57, v63, v58
	v_mul_f32_e32 v64, v61, v60
	v_fmac_f32_e32 v63, v62, v56
	v_fma_f32 v62, -v59, v64, v61
	v_fma_f32 v57, -v57, v63, v58
	v_fmac_f32_e32 v64, v62, v60
	v_div_fmas_f32 v56, v57, v56, v63
	v_div_fixup_f32 v54, v56, v54, 1.0
	v_fma_f32 v56, -v59, v64, v61
	s_mov_b64 vcc, s[4:5]
	v_div_fmas_f32 v56, v56, v60, v64
	v_pk_mul_f32 v[24:25], v[24:25], v[54:55] op_sel_hi:[1,0]
	v_pk_mul_f32 v[26:27], v[26:27], v[54:55] op_sel_hi:[1,0]
	v_div_fixup_f32 v56, v56, v55, 1.0
	s_waitcnt vmcnt(0)
	v_pk_mul_f32 v[24:25], v[80:81], v[24:25]
	v_pk_mul_f32 v[26:27], v[82:83], v[26:27]
	s_lshl_b64 s[4:5], s[26:27], 11
	v_cvt_pk_bf16_f32 v24, v24, v25
	v_cvt_pk_bf16_f32 v25, v26, v27
	v_pk_mul_f32 v[26:27], v[28:29], v[56:57] op_sel_hi:[1,0]
	v_pk_mul_f32 v[28:29], v[30:31], v[56:57] op_sel_hi:[1,0]
	v_lshl_add_u64 v[58:59], v[40:41], 0, s[4:5]
	s_lshl_b64 s[4:5], s[8:9], 11
	v_pk_mul_f32 v[26:27], v[80:81], v[26:27]
	v_pk_mul_f32 v[28:29], v[82:83], v[28:29]
	v_lshl_add_u64 v[60:61], v[40:41], 0, s[4:5]
	v_cvt_pk_bf16_f32 v26, v26, v27
	v_cvt_pk_bf16_f32 v27, v28, v29
	global_store_dwordx2 v[58:59], v[24:25], off
	global_store_dwordx2 v[60:61], v[26:27], off
	v_pk_mul_f32 v[16:17], v[16:17], v[54:55] op_sel_hi:[1,0]
	v_pk_mul_f32 v[18:19], v[18:19], v[54:55] op_sel_hi:[1,0]
	v_pk_mul_f32 v[20:21], v[20:21], v[56:57] op_sel_hi:[1,0]
	v_pk_mul_f32 v[22:23], v[22:23], v[56:57] op_sel_hi:[1,0]
	v_pk_mul_f32 v[12:13], v[12:13], v[54:55] op_sel_hi:[1,0]
	v_pk_mul_f32 v[14:15], v[14:15], v[54:55] op_sel_hi:[1,0]
	v_pk_mul_f32 v[8:9], v[8:9], v[56:57] op_sel_hi:[1,0]
	v_pk_mul_f32 v[10:11], v[10:11], v[56:57] op_sel_hi:[1,0]
	v_pk_mul_f32 v[0:1], v[0:1], v[54:55] op_sel_hi:[1,0]
	v_pk_mul_f32 v[2:3], v[2:3], v[54:55] op_sel_hi:[1,0]
	s_add_i32 s26, s8, s20
	v_pk_mul_f32 v[4:5], v[4:5], v[56:57] op_sel_hi:[1,0]
	v_pk_mul_f32 v[6:7], v[6:7], v[56:57] op_sel_hi:[1,0]
	s_cmpk_gt_i32 s26, 0x7fff
	v_pk_mul_f32 v[16:17], v[84:85], v[16:17]
	v_pk_mul_f32 v[18:19], v[86:87], v[18:19]
	v_pk_mul_f32 v[20:21], v[84:85], v[20:21]
	v_pk_mul_f32 v[22:23], v[86:87], v[22:23]
	v_cvt_pk_bf16_f32 v16, v16, v17
	v_cvt_pk_bf16_f32 v17, v18, v19
	v_cvt_pk_bf16_f32 v18, v20, v21
	v_cvt_pk_bf16_f32 v19, v22, v23
	global_store_dwordx2 v[58:59], v[16:17], off offset:512
	global_store_dwordx2 v[60:61], v[18:19], off offset:512
	v_pk_mul_f32 v[12:13], v[12:13], v[88:89]
	v_pk_mul_f32 v[14:15], v[14:15], v[90:91]
	v_pk_mul_f32 v[8:9], v[8:9], v[88:89]
	v_pk_mul_f32 v[10:11], v[10:11], v[90:91]
	v_cvt_pk_bf16_f32 v12, v12, v13
	v_cvt_pk_bf16_f32 v13, v14, v15
	v_cvt_pk_bf16_f32 v8, v8, v9
	v_cvt_pk_bf16_f32 v9, v10, v11
	global_store_dwordx2 v[58:59], v[12:13], off offset:1024
	global_store_dwordx2 v[60:61], v[8:9], off offset:1024
	v_pk_mul_f32 v[0:1], v[0:1], v[92:93]
	v_pk_mul_f32 v[2:3], v[2:3], v[94:95]
	v_pk_mul_f32 v[4:5], v[4:5], v[92:93]
	v_pk_mul_f32 v[6:7], v[6:7], v[94:95]
	v_cvt_pk_bf16_f32 v0, v0, v1
	v_cvt_pk_bf16_f32 v1, v2, v3
	v_cvt_pk_bf16_f32 v2, v4, v5
	v_cvt_pk_bf16_f32 v3, v6, v7
	global_store_dwordx2 v[58:59], v[0:1], off offset:1536
	global_store_dwordx2 v[60:61], v[2:3], off offset:1536
	s_cbranch_scc0 .LBB0_81
